# P9 context rows: two groups of partial-tile loads in flight (on top of the context-row spread)
# baseline (speedup 1.0000x reference)
; #define GAS __attribute__((address_space(1)))
;     ...
;         if (nparts > 0 && m >= ML) {
;             for (int p = 0; p < nparts; p += 4) {
;                 const GAS f32x4* pr = (const GAS f32x4*)(parts + (size_t)p * (512 * 1024) + (size_t)(m - ML) * DM) + F.lane;
;                 f32x4 w[4][4];
; #pragma unroll
;                 for (int q = 0; q < 4; ++q)
; #pragma unroll
;                     for (int j = 0; j < 4; ++j) w[q][j] = pr[(size_t)q * (512 * 1024 / 4) + 64 * j];
; #pragma unroll
;                 for (int j = 0; j < 4; ++j) v[j] += (w[0][j] + w[1][j]) + (w[2][j] + w[3][j]); }
.LBB0_166:
	v_readlane_b32 s14, v243, 9
	v_readlane_b32 s15, v243, 10
	s_add_i32 s14, s0, 0xffffc000
	s_mov_b32 s1, s15
	s_lshl_b64 s[14:15], s[14:15], 12
	s_add_u32 s18, s16, s14
	v_writelane_b32 v243, s0, 9
	s_addc_u32 s19, s17, s15
	v_lshl_add_u64 v[66:67], s[18:19], 0, v[0:1]
	v_writelane_b32 v243, s1, 10
	s_mov_b32 s1, 0x200000
	v_add_co_u32_e32 v62, vcc, s1, v66
	s_mov_b32 s1, 0x400000
	s_nop 0
	v_addc_co_u32_e32 v63, vcc, 0, v67, vcc
	v_add_co_u32_e32 v80, vcc, s1, v66
	s_mov_b32 s1, 0x600000
	s_nop 0
	v_addc_co_u32_e32 v81, vcc, 0, v67, vcc
	s_mov_b64 s[18:19], 0x200000
	v_mov_b64_e32 v[216:217], v[66:67]
	global_load_dwordx4 v[104:107], v[216:217], off
	global_load_dwordx4 v[108:111], v[216:217], off offset:1024
	global_load_dwordx4 v[112:115], v[216:217], off offset:2048
	global_load_dwordx4 v[116:119], v[216:217], off offset:3072
	v_lshl_add_u64 v[216:217], v[216:217], 0, s[18:19]
	global_load_dwordx4 v[120:123], v[216:217], off
	global_load_dwordx4 v[124:127], v[216:217], off offset:1024
	global_load_dwordx4 v[128:131], v[216:217], off offset:2048
	global_load_dwordx4 v[132:135], v[216:217], off offset:3072
	v_lshl_add_u64 v[216:217], v[216:217], 0, s[18:19]
	global_load_dwordx4 v[136:139], v[216:217], off
	global_load_dwordx4 v[140:143], v[216:217], off offset:1024
	global_load_dwordx4 v[144:147], v[216:217], off offset:2048
	global_load_dwordx4 v[148:151], v[216:217], off offset:3072
	v_lshl_add_u64 v[216:217], v[216:217], 0, s[18:19]
	global_load_dwordx4 v[152:155], v[216:217], off
	global_load_dwordx4 v[156:159], v[216:217], off offset:1024
	global_load_dwordx4 v[160:163], v[216:217], off offset:2048
	global_load_dwordx4 v[164:167], v[216:217], off offset:3072
	v_lshl_add_u64 v[216:217], v[216:217], 0, s[18:19]
	global_load_dwordx4 v[34:37], v[216:217], off
	global_load_dwordx4 v[38:41], v[216:217], off offset:1024
	global_load_dwordx4 v[42:45], v[216:217], off offset:2048
	global_load_dwordx4 v[46:49], v[216:217], off offset:3072
	v_lshl_add_u64 v[216:217], v[216:217], 0, s[18:19]
	global_load_dwordx4 v[50:53], v[216:217], off
	global_load_dwordx4 v[54:57], v[216:217], off offset:1024
	global_load_dwordx4 v[58:61], v[216:217], off offset:2048
	global_load_dwordx4 v[62:65], v[216:217], off offset:3072
	v_lshl_add_u64 v[216:217], v[216:217], 0, s[18:19]
	global_load_dwordx4 v[68:71], v[216:217], off
	global_load_dwordx4 v[72:75], v[216:217], off offset:1024
	global_load_dwordx4 v[76:79], v[216:217], off offset:2048
	global_load_dwordx4 v[88:91], v[216:217], off offset:3072
	v_lshl_add_u64 v[216:217], v[216:217], 0, s[18:19]
	global_load_dwordx4 v[92:95], v[216:217], off
	global_load_dwordx4 v[96:99], v[216:217], off offset:1024
	global_load_dwordx4 v[208:211], v[216:217], off offset:2048
	global_load_dwordx4 v[212:215], v[216:217], off offset:3072
	v_lshl_add_u64 v[216:217], v[216:217], 0, s[18:19]
	s_waitcnt vmcnt(16)
	v_pk_add_f32 v[218:219], v[104:105], v[120:121]
	v_pk_add_f32 v[220:221], v[136:137], v[152:153]
	v_pk_add_f32 v[218:219], v[218:219], v[220:221]
	v_pk_add_f32 v[30:31], v[30:31], v[218:219]
	v_pk_add_f32 v[218:219], v[106:107], v[122:123]
	v_pk_add_f32 v[220:221], v[138:139], v[154:155]
	v_pk_add_f32 v[218:219], v[218:219], v[220:221]
	v_pk_add_f32 v[32:33], v[32:33], v[218:219]
	v_pk_add_f32 v[218:219], v[108:109], v[124:125]
	v_pk_add_f32 v[220:221], v[140:141], v[156:157]
	v_pk_add_f32 v[218:219], v[218:219], v[220:221]
	v_pk_add_f32 v[26:27], v[26:27], v[218:219]
	v_pk_add_f32 v[218:219], v[110:111], v[126:127]
	v_pk_add_f32 v[220:221], v[142:143], v[158:159]
	v_pk_add_f32 v[218:219], v[218:219], v[220:221]
	v_pk_add_f32 v[28:29], v[28:29], v[218:219]
	v_pk_add_f32 v[218:219], v[112:113], v[128:129]
	v_pk_add_f32 v[220:221], v[144:145], v[160:161]
	v_pk_add_f32 v[218:219], v[218:219], v[220:221]
	v_pk_add_f32 v[22:23], v[22:23], v[218:219]
	v_pk_add_f32 v[218:219], v[114:115], v[130:131]
	v_pk_add_f32 v[220:221], v[146:147], v[162:163]
	v_pk_add_f32 v[218:219], v[218:219], v[220:221]
	v_pk_add_f32 v[24:25], v[24:25], v[218:219]
	v_pk_add_f32 v[218:219], v[116:117], v[132:133]
	v_pk_add_f32 v[220:221], v[148:149], v[164:165]
	v_pk_add_f32 v[218:219], v[218:219], v[220:221]
	v_pk_add_f32 v[18:19], v[18:19], v[218:219]
	v_pk_add_f32 v[218:219], v[118:119], v[134:135]
	v_pk_add_f32 v[220:221], v[150:151], v[166:167]
	v_pk_add_f32 v[218:219], v[218:219], v[220:221]
	v_pk_add_f32 v[20:21], v[20:21], v[218:219]
	global_load_dwordx4 v[104:107], v[216:217], off
	global_load_dwordx4 v[108:111], v[216:217], off offset:1024
	global_load_dwordx4 v[112:115], v[216:217], off offset:2048
	global_load_dwordx4 v[116:119], v[216:217], off offset:3072
	v_lshl_add_u64 v[216:217], v[216:217], 0, s[18:19]
	global_load_dwordx4 v[120:123], v[216:217], off
	global_load_dwordx4 v[124:127], v[216:217], off offset:1024
	global_load_dwordx4 v[128:131], v[216:217], off offset:2048
	global_load_dwordx4 v[132:135], v[216:217], off offset:3072
	v_lshl_add_u64 v[216:217], v[216:217], 0, s[18:19]
	global_load_dwordx4 v[136:139], v[216:217], off
	global_load_dwordx4 v[140:143], v[216:217], off offset:1024
	global_load_dwordx4 v[144:147], v[216:217], off offset:2048
	global_load_dwordx4 v[148:151], v[216:217], off offset:3072
	v_lshl_add_u64 v[216:217], v[216:217], 0, s[18:19]
	global_load_dwordx4 v[152:155], v[216:217], off
	global_load_dwordx4 v[156:159], v[216:217], off offset:1024
	global_load_dwordx4 v[160:163], v[216:217], off offset:2048
	global_load_dwordx4 v[164:167], v[216:217], off offset:3072
	v_lshl_add_u64 v[216:217], v[216:217], 0, s[18:19]
	s_waitcnt vmcnt(16)
; #define GAS __attribute__((address_space(1)))
;     ...
;         if (nparts > 0 && m >= ML) {
;             for (int p = 0; p < nparts; p += 4) {
;                 const GAS f32x4* pr = (const GAS f32x4*)(parts + (size_t)p * (512 * 1024) + (size_t)(m - ML) * DM) + F.lane;
;                 f32x4 w[4][4];
; #pragma unroll
;                 for (int q = 0; q < 4; ++q)
; #pragma unroll
;                     for (int j = 0; j < 4; ++j) w[q][j] = pr[(size_t)q * (512 * 1024 / 4) + 64 * j];
; #pragma unroll
;                 for (int j = 0; j < 4; ++j) v[j] += (w[0][j] + w[1][j]) + (w[2][j] + w[3][j]); }
;             GAS f32x4* cr = (GAS f32x4*)((float*)(F.ws + WS_CTXRES) + (size_t)(m - ML) * DM) + F.lane;
; #pragma unroll
;             for (int j = 0; j < 4; ++j) cr[64 * j] = v[j];
	v_pk_add_f32 v[218:219], v[34:35], v[50:51]
	v_pk_add_f32 v[220:221], v[68:69], v[92:93]
	v_pk_add_f32 v[218:219], v[218:219], v[220:221]
	v_pk_add_f32 v[30:31], v[30:31], v[218:219]
	v_pk_add_f32 v[218:219], v[36:37], v[52:53]
	v_pk_add_f32 v[220:221], v[70:71], v[94:95]
	v_pk_add_f32 v[218:219], v[218:219], v[220:221]
	v_pk_add_f32 v[32:33], v[32:33], v[218:219]
	v_pk_add_f32 v[218:219], v[38:39], v[54:55]
	v_pk_add_f32 v[220:221], v[72:73], v[96:97]
	v_pk_add_f32 v[218:219], v[218:219], v[220:221]
	v_pk_add_f32 v[26:27], v[26:27], v[218:219]
	v_pk_add_f32 v[218:219], v[40:41], v[56:57]
	v_pk_add_f32 v[220:221], v[74:75], v[98:99]
	v_pk_add_f32 v[218:219], v[218:219], v[220:221]
	v_pk_add_f32 v[28:29], v[28:29], v[218:219]
	v_pk_add_f32 v[218:219], v[42:43], v[58:59]
	v_pk_add_f32 v[220:221], v[76:77], v[208:209]
	v_pk_add_f32 v[218:219], v[218:219], v[220:221]
	v_pk_add_f32 v[22:23], v[22:23], v[218:219]
	v_pk_add_f32 v[218:219], v[44:45], v[60:61]
	v_pk_add_f32 v[220:221], v[78:79], v[210:211]
	v_pk_add_f32 v[218:219], v[218:219], v[220:221]
	v_pk_add_f32 v[24:25], v[24:25], v[218:219]
	v_pk_add_f32 v[218:219], v[46:47], v[62:63]
	v_pk_add_f32 v[220:221], v[88:89], v[212:213]
	v_pk_add_f32 v[218:219], v[218:219], v[220:221]
	v_pk_add_f32 v[18:19], v[18:19], v[218:219]
	v_pk_add_f32 v[218:219], v[48:49], v[64:65]
	v_pk_add_f32 v[220:221], v[90:91], v[214:215]
	v_pk_add_f32 v[218:219], v[218:219], v[220:221]
	v_pk_add_f32 v[20:21], v[20:21], v[218:219]
	global_load_dwordx4 v[34:37], v[216:217], off
	global_load_dwordx4 v[38:41], v[216:217], off offset:1024
	global_load_dwordx4 v[42:45], v[216:217], off offset:2048
	global_load_dwordx4 v[46:49], v[216:217], off offset:3072
	v_lshl_add_u64 v[216:217], v[216:217], 0, s[18:19]
	global_load_dwordx4 v[50:53], v[216:217], off
	global_load_dwordx4 v[54:57], v[216:217], off offset:1024
	global_load_dwordx4 v[58:61], v[216:217], off offset:2048
	global_load_dwordx4 v[62:65], v[216:217], off offset:3072
	v_lshl_add_u64 v[216:217], v[216:217], 0, s[18:19]
	global_load_dwordx4 v[68:71], v[216:217], off
	global_load_dwordx4 v[72:75], v[216:217], off offset:1024
	global_load_dwordx4 v[76:79], v[216:217], off offset:2048
	global_load_dwordx4 v[88:91], v[216:217], off offset:3072
	v_lshl_add_u64 v[216:217], v[216:217], 0, s[18:19]
	global_load_dwordx4 v[92:95], v[216:217], off
	global_load_dwordx4 v[96:99], v[216:217], off offset:1024
	global_load_dwordx4 v[208:211], v[216:217], off offset:2048
	global_load_dwordx4 v[212:215], v[216:217], off offset:3072
	v_lshl_add_u64 v[216:217], v[216:217], 0, s[18:19]
	s_waitcnt vmcnt(16)
	v_pk_add_f32 v[218:219], v[104:105], v[120:121]
	v_pk_add_f32 v[220:221], v[136:137], v[152:153]
	v_pk_add_f32 v[218:219], v[218:219], v[220:221]
	v_pk_add_f32 v[30:31], v[30:31], v[218:219]
	v_pk_add_f32 v[218:219], v[106:107], v[122:123]
	v_pk_add_f32 v[220:221], v[138:139], v[154:155]
	v_pk_add_f32 v[218:219], v[218:219], v[220:221]
	v_pk_add_f32 v[32:33], v[32:33], v[218:219]
	v_pk_add_f32 v[218:219], v[108:109], v[124:125]
	v_pk_add_f32 v[220:221], v[140:141], v[156:157]
	v_pk_add_f32 v[218:219], v[218:219], v[220:221]
	v_pk_add_f32 v[26:27], v[26:27], v[218:219]
	v_pk_add_f32 v[218:219], v[110:111], v[126:127]
	v_pk_add_f32 v[220:221], v[142:143], v[158:159]
	v_pk_add_f32 v[218:219], v[218:219], v[220:221]
	v_pk_add_f32 v[28:29], v[28:29], v[218:219]
	v_pk_add_f32 v[218:219], v[112:113], v[128:129]
	v_pk_add_f32 v[220:221], v[144:145], v[160:161]
	v_pk_add_f32 v[218:219], v[218:219], v[220:221]
	v_pk_add_f32 v[22:23], v[22:23], v[218:219]
	v_pk_add_f32 v[218:219], v[114:115], v[130:131]
	v_pk_add_f32 v[220:221], v[146:147], v[162:163]
	v_pk_add_f32 v[218:219], v[218:219], v[220:221]
	v_pk_add_f32 v[24:25], v[24:25], v[218:219]
	v_pk_add_f32 v[218:219], v[116:117], v[132:133]
	v_pk_add_f32 v[220:221], v[148:149], v[164:165]
	v_pk_add_f32 v[218:219], v[218:219], v[220:221]
	v_pk_add_f32 v[18:19], v[18:19], v[218:219]
	v_pk_add_f32 v[218:219], v[118:119], v[134:135]
	v_pk_add_f32 v[220:221], v[150:151], v[166:167]
	v_pk_add_f32 v[218:219], v[218:219], v[220:221]
	v_pk_add_f32 v[20:21], v[20:21], v[218:219]
	s_waitcnt vmcnt(0)
	v_pk_add_f32 v[218:219], v[34:35], v[50:51]
	v_pk_add_f32 v[220:221], v[68:69], v[92:93]
	v_pk_add_f32 v[218:219], v[218:219], v[220:221]
	v_pk_add_f32 v[30:31], v[30:31], v[218:219]
	v_pk_add_f32 v[218:219], v[36:37], v[52:53]
	v_pk_add_f32 v[220:221], v[70:71], v[94:95]
	v_pk_add_f32 v[218:219], v[218:219], v[220:221]
	v_pk_add_f32 v[32:33], v[32:33], v[218:219]
	v_pk_add_f32 v[218:219], v[38:39], v[54:55]
	v_pk_add_f32 v[220:221], v[72:73], v[96:97]
	v_pk_add_f32 v[218:219], v[218:219], v[220:221]
	v_pk_add_f32 v[26:27], v[26:27], v[218:219]
	v_pk_add_f32 v[218:219], v[40:41], v[56:57]
	v_pk_add_f32 v[220:221], v[74:75], v[98:99]
	v_pk_add_f32 v[218:219], v[218:219], v[220:221]
	v_pk_add_f32 v[28:29], v[28:29], v[218:219]
	v_pk_add_f32 v[218:219], v[42:43], v[58:59]
	v_pk_add_f32 v[220:221], v[76:77], v[208:209]
	v_pk_add_f32 v[218:219], v[218:219], v[220:221]
	v_pk_add_f32 v[22:23], v[22:23], v[218:219]
	v_pk_add_f32 v[218:219], v[44:45], v[60:61]
	v_pk_add_f32 v[220:221], v[78:79], v[210:211]
	v_pk_add_f32 v[218:219], v[218:219], v[220:221]
	v_pk_add_f32 v[24:25], v[24:25], v[218:219]
	v_pk_add_f32 v[218:219], v[46:47], v[62:63]
	v_pk_add_f32 v[220:221], v[88:89], v[212:213]
	v_pk_add_f32 v[218:219], v[218:219], v[220:221]
	v_pk_add_f32 v[18:19], v[18:19], v[218:219]
	v_pk_add_f32 v[218:219], v[48:49], v[64:65]
	v_pk_add_f32 v[220:221], v[90:91], v[214:215]
	v_pk_add_f32 v[218:219], v[218:219], v[220:221]
	v_pk_add_f32 v[20:21], v[20:21], v[218:219]
	v_lshl_add_u64 v[34:35], v[82:83], 0, s[14:15]
	global_store_dwordx4 v[34:35], v[30:33], off
	global_store_dwordx4 v[34:35], v[26:29], off offset:1024
	global_store_dwordx4 v[34:35], v[22:25], off offset:2048
	global_store_dwordx4 v[34:35], v[18:21], off offset:3072
	s_branch .LBB0_160
